# mini_gemm (K=2816, P4/P13): 3-trip K loop fully unrolled with all operand loads in flight; sample_norm_rows (P5/P11): gain/scale/shift loads of column chunks 1..3 issued with chunk 0's instead of seri
# baseline (speedup 1.0000x reference)
; #define lane opq(lane_now())
; __device__ __forceinline__ f32x4 mini_partial(const bf16* A, const bf16* Bt, int K, int row0, int col0, int ks, int lane) {
;     const int kq = K >> 2;
;     const bf16* ap = A + (size_t)(MPR + row0 + (lane & 15)) * K + ks * kq + (lane >> 4) * 8;
;     const bf16* bp = Bt + (size_t)(col0 + (lane & 15)) * K + ks * kq + (lane >> 4) * 8;
;     f32x4 acc = {0.f, 0.f, 0.f, 0.f};
; #pragma unroll 1
;     for (int k0 = 0; k0 < kq; k0 += 256) {
;         bf16x8 a[8], b[8];
; #pragma unroll
;         for (int i = 0; i < 8; ++i) if (k0 + 32 * i < kq) { a[i] = *(const bf16x8*)(ap + k0 + 32 * i); b[i] = *(const bf16x8*)(bp + k0 + 32 * i); }
; #pragma unroll
;         for (int i = 0; i < 8; ++i) if (k0 + 32 * i < kq) acc = __builtin_amdgcn_mfma_f32_16x16x32_bf16(b[i], a[i], acc, 0, 0, 0);
;     }
;     return acc;
.LBB0_608:
	global_load_dwordx4 v[44:47], v[80:81], off offset:-256
	global_load_dwordx4 v[48:51], v[78:79], off offset:-256
	global_load_dwordx4 v[32:35], v[80:81], off offset:-192
	global_load_dwordx4 v[40:43], v[78:79], off offset:-192
	global_load_dwordx4 v[36:39], v[80:81], off offset:-128
	global_load_dwordx4 v[28:31], v[78:79], off offset:-128
	global_load_dwordx4 v[60:63], v[80:81], off offset:-64
	global_load_dwordx4 v[24:27], v[78:79], off offset:-64
	global_load_dwordx4 v[68:71], v[80:81], off
	global_load_dwordx4 v[56:59], v[78:79], off
	global_load_dwordx4 v[64:67], v[80:81], off offset:64
	global_load_dwordx4 v[52:55], v[78:79], off offset:64
	global_load_dwordx4 v[16:19], v[80:81], off offset:128
	global_load_dwordx4 v[8:11], v[78:79], off offset:128
	global_load_dwordx4 v[12:15], v[80:81], off offset:192
	global_load_dwordx4 v[20:23], v[78:79], off offset:192
	global_load_dwordx4 v[92:95], v[80:81], off offset:256
	global_load_dwordx4 v[96:99], v[78:79], off offset:256
	global_load_dwordx4 v[100:103], v[80:81], off offset:320
	global_load_dwordx4 v[104:107], v[78:79], off offset:320
	global_load_dwordx4 v[108:111], v[80:81], off offset:384
	global_load_dwordx4 v[112:115], v[78:79], off offset:384
	global_load_dwordx4 v[116:119], v[80:81], off offset:448
	global_load_dwordx4 v[120:123], v[78:79], off offset:448
	global_load_dwordx4 v[124:127], v[80:81], off offset:512
	global_load_dwordx4 v[128:131], v[78:79], off offset:512
	global_load_dwordx4 v[132:135], v[80:81], off offset:576
	global_load_dwordx4 v[136:139], v[78:79], off offset:576
	global_load_dwordx4 v[140:143], v[80:81], off offset:640
	global_load_dwordx4 v[144:147], v[78:79], off offset:640
	global_load_dwordx4 v[148:151], v[80:81], off offset:704
	global_load_dwordx4 v[152:155], v[78:79], off offset:704
	global_load_dwordx4 v[156:159], v[80:81], off offset:768
	global_load_dwordx4 v[160:163], v[78:79], off offset:768
	global_load_dwordx4 v[168:171], v[80:81], off offset:832
	global_load_dwordx4 v[172:175], v[78:79], off offset:832
	global_load_dwordx4 v[176:179], v[80:81], off offset:896
	global_load_dwordx4 v[180:183], v[78:79], off offset:896
	global_load_dwordx4 v[184:187], v[80:81], off offset:960
	global_load_dwordx4 v[188:191], v[78:79], off offset:960
	global_load_dwordx4 v[192:195], v[80:81], off offset:1024
	global_load_dwordx4 v[196:199], v[78:79], off offset:1024
	global_load_dwordx4 v[200:203], v[80:81], off offset:1088
	global_load_dwordx4 v[204:207], v[78:79], off offset:1088
	s_waitcnt vmcnt(42)
	v_mfma_f32_16x16x32_bf16 v[4:7], v[44:47], v[48:51], v[4:7]
	s_waitcnt vmcnt(40)
	v_mfma_f32_16x16x32_bf16 v[4:7], v[32:35], v[40:43], v[4:7]
	s_waitcnt vmcnt(38)
	v_mfma_f32_16x16x32_bf16 v[4:7], v[36:39], v[28:31], v[4:7]
	s_waitcnt vmcnt(36)
	v_mfma_f32_16x16x32_bf16 v[4:7], v[60:63], v[24:27], v[4:7]
	s_waitcnt vmcnt(34)
	v_mfma_f32_16x16x32_bf16 v[4:7], v[68:71], v[56:59], v[4:7]
	s_waitcnt vmcnt(32)
	v_mfma_f32_16x16x32_bf16 v[4:7], v[64:67], v[52:55], v[4:7]
	s_waitcnt vmcnt(30)
	v_mfma_f32_16x16x32_bf16 v[4:7], v[16:19], v[8:11], v[4:7]
	s_waitcnt vmcnt(28)
	v_mfma_f32_16x16x32_bf16 v[4:7], v[12:15], v[20:23], v[4:7]
	s_waitcnt vmcnt(26)
	v_mfma_f32_16x16x32_bf16 v[4:7], v[92:95], v[96:99], v[4:7]
	s_waitcnt vmcnt(24)
	v_mfma_f32_16x16x32_bf16 v[4:7], v[100:103], v[104:107], v[4:7]
	s_waitcnt vmcnt(22)
	v_mfma_f32_16x16x32_bf16 v[4:7], v[108:111], v[112:115], v[4:7]
	s_waitcnt vmcnt(20)
	v_mfma_f32_16x16x32_bf16 v[4:7], v[116:119], v[120:123], v[4:7]
	s_waitcnt vmcnt(18)
	v_mfma_f32_16x16x32_bf16 v[4:7], v[124:127], v[128:131], v[4:7]
	s_waitcnt vmcnt(16)
	v_mfma_f32_16x16x32_bf16 v[4:7], v[132:135], v[136:139], v[4:7]
	s_waitcnt vmcnt(14)
	v_mfma_f32_16x16x32_bf16 v[4:7], v[140:143], v[144:147], v[4:7]
	s_waitcnt vmcnt(12)
	v_mfma_f32_16x16x32_bf16 v[4:7], v[148:151], v[152:155], v[4:7]
	s_waitcnt vmcnt(10)
	v_mfma_f32_16x16x32_bf16 v[4:7], v[156:159], v[160:163], v[4:7]
	s_waitcnt vmcnt(8)
	v_mfma_f32_16x16x32_bf16 v[4:7], v[168:171], v[172:175], v[4:7]
	s_waitcnt vmcnt(6)
	v_mfma_f32_16x16x32_bf16 v[4:7], v[176:179], v[180:183], v[4:7]
	s_waitcnt vmcnt(4)
	v_mfma_f32_16x16x32_bf16 v[4:7], v[184:187], v[188:191], v[4:7]
	s_waitcnt vmcnt(2)
	v_mfma_f32_16x16x32_bf16 v[4:7], v[192:195], v[196:199], v[4:7]
	s_waitcnt vmcnt(0)
	v_mfma_f32_16x16x32_bf16 v[4:7], v[200:203], v[204:207], v[4:7]
	s_nop 7

; __device__ __forceinline__ float rsq_f(float x) { return __builtin_amdgcn_rsqf(x); }
; __device__ __forceinline__ float* karg_out() { return *(volatile KAS fptr_t*)((const KAS char*)__builtin_amdgcn_kernarg_segment_ptr() + 256); }
; __device__ __forceinline__ unsigned char* karg_ws() { return *(volatile KAS ucptr_t*)((const KAS char*)__builtin_amdgcn_kernarg_segment_ptr() + 264); }
; #define lane opq(lane_now())
; template <int MODE>
; __device__ __forceinline__ void sample_norm_rows(const float* gvec, int ish, int gw, int lane) {
;     if (gw >= NS) return;
;     const int row = MPR + gw; float* X = karg_out() + (size_t)row * D;
;     f32x4 v[4]; float s = 0.f;
; #pragma unroll
;     for (int j = 0; j < 4; ++j) { v[j] = *(const f32x4*)(X + 4 * (lane + 64 * j)); s += (v[j][0] * v[j][0] + v[j][1] * v[j][1]) + (v[j][2] * v[j][2] + v[j][3] * v[j][3]); }
;     const float rstd = rsq_f(wave_sum(s) * (1.f / D) + EPS);
;     const float* sh = (const float*)(karg_ws() + WS_ADA) + (size_t)cond_of_row(row) * NADA + ish * D;
.LBB0_670:
	s_or_b64 exec, exec, s[4:5]
	s_waitcnt lgkmcnt(0)
	s_barrier
	s_load_dwordx2 s[10:11], s[0:1], 0x68
	s_cmpk_lt_i32 s72, 0x80
	s_cselect_b64 s[4:5], -1, 0
	v_mov_b32_e32 v0, v166
	v_writelane_b32 v238, s4, 8
	s_cmpk_gt_i32 s72, 0x7f
	s_nop 0
	v_writelane_b32 v238, s5, 9
	s_cbranch_scc1 .LBB0_672
	s_load_dwordx2 s[4:5], s[0:1], 0x100
	s_add_i32 s8, s72, 0x4000
	s_ashr_i32 s9, s8, 31
	v_lshlrev_b32_e32 v8, 2, v0
	s_lshl_b64 s[6:7], s[8:9], 12
	s_waitcnt lgkmcnt(0)
	s_add_u32 s4, s4, s6
	v_ashrrev_i32_e32 v9, 31, v8
	s_addc_u32 s5, s5, s7
	v_lshlrev_b64 v[26:27], 2, v[8:9]
	v_lshl_add_u64 v[18:19], s[4:5], 0, v[26:27]
	global_load_dwordx4 v[10:13], v[18:19], off
	global_load_dwordx4 v[14:17], v[18:19], off offset:1024
	global_load_dwordx4 v[0:3], v[18:19], off offset:3072
	global_load_dwordx4 v[4:7], v[18:19], off offset:2048
	s_load_dwordx2 s[4:5], s[0:1], 0x108
	s_ashr_i32 s6, s8, 11
	s_add_i32 s7, s72, 8
	s_cmp_lt_i32 s72, 0
	s_cselect_b32 s6, s6, s7
	s_mul_hi_i32 s7, s6, 0x9000
	s_mul_i32 s6, s6, 0x9000
	s_waitcnt lgkmcnt(0)
	s_add_u32 s6, s4, s6
	s_addc_u32 s7, s5, s7
	s_add_u32 s4, s6, 0x2903000
	s_addc_u32 s5, s7, 0
	s_add_u32 s6, s6, 0x2904000
	s_addc_u32 s7, s7, 0
	v_lshl_add_u64 v[92:93], s[6:7], 0, v[26:27]
	v_lshl_add_u64 v[30:31], s[10:11], 0, v[26:27]
	global_load_dwordx4 v[18:21], v[92:93], off
	v_lshl_add_u64 v[94:95], s[4:5], 0, v[26:27]
	global_load_dwordx4 v[22:25], v[30:31], off
	v_mov_b32_e32 v49, 0x358637bd
	global_load_dwordx4 v[26:29], v[94:95], off
	global_load_dwordx4 v[96:99], v[30:31], off offset:1024
	global_load_dwordx4 v[100:103], v[92:93], off offset:1024
	global_load_dwordx4 v[104:107], v[94:95], off offset:1024
	global_load_dwordx4 v[108:111], v[30:31], off offset:2048
	global_load_dwordx4 v[112:115], v[92:93], off offset:2048
	global_load_dwordx4 v[116:119], v[94:95], off offset:2048
	global_load_dwordx4 v[120:123], v[30:31], off offset:3072
	global_load_dwordx4 v[124:127], v[92:93], off offset:3072
	global_load_dwordx4 v[128:131], v[94:95], off offset:3072
	v_lshlrev_b64 v[34:35], 1, v[8:9]
	s_load_dwordx2 s[10:11], s[0:1], 0x108
	s_lshl_b64 s[8:9], s[8:9], 11
	s_mov_b32 s12, 0x3000000
	v_add_u32_e32 v32, 0x100, v8
	v_ashrrev_i32_e32 v33, 31, v32
	s_waitcnt lgkmcnt(0)
	s_add_u32 s10, s10, s8
	s_addc_u32 s11, s11, s9
	v_lshl_add_u64 v[36:37], s[10:11], 0, v[34:35]
	v_add_co_u32_e32 v36, vcc, s12, v36
	v_lshlrev_b64 v[32:33], 2, v[32:33]
	s_nop 0
	v_addc_co_u32_e32 v37, vcc, 0, v37, vcc
	s_waitcnt vmcnt(15)
	v_pk_mul_f32 v[38:39], v[12:13], v[12:13]
	v_pk_mul_f32 v[40:41], v[10:11], v[10:11]
	s_waitcnt vmcnt(14)
	v_pk_mul_f32 v[42:43], v[16:17], v[16:17]
	v_pk_mul_f32 v[44:45], v[14:15], v[14:15]
	v_pk_mov_b32 v[50:51], v[40:41], v[38:39] op_sel:[1,0]
	v_mov_b32_e32 v41, v39
	v_pk_mov_b32 v[38:39], v[44:45], v[42:43] op_sel:[1,0]
	v_mov_b32_e32 v45, v43
	s_waitcnt vmcnt(12)
	v_mul_f32_e32 v46, v5, v5
	v_mul_f32_e32 v48, v7, v7
	v_pk_add_f32 v[40:41], v[50:51], v[40:41]
	v_pk_add_f32 v[38:39], v[38:39], v[44:45]
	v_mul_f32_e32 v9, v0, v0
	v_mul_f32_e32 v52, v1, v1
	v_mul_f32_e32 v53, v2, v2
	v_mul_f32_e32 v54, v3, v3
	v_pk_fma_f32 v[42:43], v[4:5], v[4:5], v[46:47] op_sel_hi:[1,1,0]
	v_pk_fma_f32 v[46:47], v[6:7], v[6:7], v[48:49] op_sel_hi:[1,1,0]
	v_pk_add_f32 v[40:41], v[40:41], v[40:41] op_sel:[0,1] op_sel_hi:[1,0]
	v_pk_add_f32 v[38:39], v[38:39], v[38:39] op_sel:[0,1] op_sel_hi:[1,0]
	v_mov_b32_e32 v43, v53
	v_mov_b32_e32 v47, v54
	v_mov_b32_e32 v41, v9
	v_mov_b32_e32 v39, v52
	v_pk_add_f32 v[42:43], v[42:43], v[46:47]
	v_pk_add_f32 v[38:39], v[40:41], v[38:39]
	s_waitcnt vmcnt(11)
; __device__ __forceinline__ unsigned pk2(float lo, float hi) { f32x2_t v = {lo, hi}; bf16x2_t b = __builtin_convertvector(v, bf16x2_t); return __builtin_bit_cast(unsigned, b); }
; __device__ __forceinline__ float rsq_f(float x) { return __builtin_amdgcn_rsqf(x); }
; __device__ __forceinline__ unsigned char* karg_ws() { return *(volatile KAS ucptr_t*)((const KAS char*)__builtin_amdgcn_kernarg_segment_ptr() + 264); }
; #define lane opq(lane_now())
; template <int MODE>
; __device__ __forceinline__ void sample_norm_rows(const float* gvec, int ish, int gw, int lane) {
;     ...
;     const float rstd = rsq_f(wave_sum(s) * (1.f / D) + EPS);
;     const float* sh = (const float*)(karg_ws() + WS_ADA) + (size_t)cond_of_row(row) * NADA + ish * D;
; #pragma unroll
;     for (int j = 0; j < 4; ++j) { const int col = 4 * (lane + 64 * j); const f32x4 g = *(const f32x4*)(gvec + col);
;         if (MODE == 0) { const f32x4 y = (v[j] * rstd * g) * (*(const f32x4*)(sh + D + col) + 1.f) + *(const f32x4*)(sh + col);
;             u32x2 o; o.x = pk2(y[0], y[1]); o.y = pk2(y[2], y[3]); *(u32x2*)((bf16*)(karg_ws() + WS_H) + (size_t)row * D + col) = o; }
;         else *(f32x4*)(X + col) = v[j] * rstd * g; }
	v_pk_add_f32 v[20:21], v[20:21], 1.0 op_sel_hi:[1,0]
	v_pk_add_f32 v[38:39], v[38:39], v[42:43]
	v_pk_add_f32 v[18:19], v[18:19], 1.0 op_sel_hi:[1,0]
	v_add_f32_e32 v9, v38, v39
	s_nop 1
	v_add_f32_dpp v9, v9, v9 quad_perm:[1,0,3,2] row_mask:0xf bank_mask:0xf bound_ctrl:1
	s_nop 1
	v_add_f32_dpp v9, v9, v9 quad_perm:[2,3,0,1] row_mask:0xf bank_mask:0xf bound_ctrl:1
	s_nop 1
	v_add_f32_dpp v9, v9, v9 row_half_mirror row_mask:0xf bank_mask:0xf bound_ctrl:1
	s_nop 1
	v_add_f32_dpp v9, v9, v9 row_mirror row_mask:0xf bank_mask:0xf bound_ctrl:1
	s_nop 0
	v_readlane_b32 s13, v9, 16
	v_readlane_b32 s14, v9, 48
	v_readlane_b32 s10, v9, 0
	v_readlane_b32 s11, v9, 32
	v_mov_b32_e32 v38, s13
	v_mov_b32_e32 v39, s14
	v_pk_add_f32 v[38:39], s[10:11], v[38:39]
	s_nop 0
	v_add_f32_e32 v9, v38, v39
	v_fmac_f32_e32 v49, 0x3a800000, v9
	v_rsq_f32_e32 v38, v49
	s_nop 0
	v_pk_mul_f32 v[12:13], v[12:13], v[38:39] op_sel_hi:[1,0]
	v_pk_mul_f32 v[10:11], v[10:11], v[38:39] op_sel_hi:[1,0]
	s_waitcnt vmcnt(10)
	v_pk_mul_f32 v[12:13], v[24:25], v[12:13]
	v_pk_mul_f32 v[10:11], v[22:23], v[10:11]
	s_waitcnt vmcnt(9)
	v_pk_fma_f32 v[12:13], v[20:21], v[12:13], v[28:29]
	v_pk_fma_f32 v[10:11], v[18:19], v[10:11], v[26:27]
	v_cvt_pk_bf16_f32 v10, v10, v11
	v_cvt_pk_bf16_f32 v11, v12, v13
	global_store_dwordx2 v[36:37], v[10:11], off
	v_pk_mul_f32 v[16:17], v[16:17], v[38:39] op_sel_hi:[1,0]
	s_load_dwordx2 s[10:11], s[0:1], 0x108
	v_pk_mul_f32 v[14:15], v[14:15], v[38:39] op_sel_hi:[1,0]
	v_add_u32_e32 v26, 0x200, v8
	v_ashrrev_i32_e32 v27, 31, v26
	v_lshlrev_b64 v[26:27], 2, v[26:27]
	s_waitcnt lgkmcnt(0)
	s_add_u32 s10, s10, s8
	s_addc_u32 s11, s11, s9
	v_lshl_add_u64 v[28:29], s[10:11], 0, v[34:35]
	v_add_co_u32_e32 v28, vcc, s12, v28
	v_add_u32_e32 v8, 0x300, v8
	s_nop 0
	v_addc_co_u32_e32 v29, vcc, 0, v29, vcc
	v_ashrrev_i32_e32 v9, 31, v8
	v_pk_mul_f32 v[6:7], v[6:7], v[38:39] op_sel_hi:[1,0]
	v_pk_mul_f32 v[4:5], v[4:5], v[38:39] op_sel_hi:[1,0]
	v_pk_mul_f32 v[2:3], v[2:3], v[38:39] op_sel_hi:[1,0]
	v_pk_mul_f32 v[0:1], v[0:1], v[38:39] op_sel_hi:[1,0]
	s_waitcnt vmcnt(9)
	v_pk_mul_f32 v[10:11], v[96:97], v[14:15]
	v_pk_mul_f32 v[12:13], v[98:99], v[16:17]
	s_waitcnt vmcnt(8)
	v_pk_add_f32 v[14:15], v[102:103], 1.0 op_sel_hi:[1,0]
	v_pk_add_f32 v[16:17], v[100:101], 1.0 op_sel_hi:[1,0]
	s_waitcnt vmcnt(7)
	v_pk_fma_f32 v[12:13], v[14:15], v[12:13], v[106:107]
	v_pk_fma_f32 v[10:11], v[16:17], v[10:11], v[104:105]
	v_cvt_pk_bf16_f32 v10, v10, v11
	v_cvt_pk_bf16_f32 v11, v12, v13
	global_store_dwordx2 v[28:29], v[10:11], off offset:512
	v_lshlrev_b64 v[22:23], 2, v[8:9]
	s_load_dwordx2 s[10:11], s[0:1], 0x108
	s_waitcnt lgkmcnt(0)
	s_add_u32 s10, s10, s8
	s_addc_u32 s11, s11, s9
	v_lshl_add_u64 v[8:9], s[10:11], 0, v[34:35]
	v_add_co_u32_e32 v8, vcc, s12, v8
	s_waitcnt vmcnt(7)
	v_pk_mul_f32 v[4:5], v[4:5], v[108:109]
	v_pk_mul_f32 v[6:7], v[6:7], v[110:111]
	s_waitcnt vmcnt(6)
	v_pk_add_f32 v[10:11], v[114:115], 1.0 op_sel_hi:[1,0]
	v_pk_add_f32 v[12:13], v[112:113], 1.0 op_sel_hi:[1,0]
	s_waitcnt vmcnt(5)
	v_pk_fma_f32 v[6:7], v[6:7], v[10:11], v[118:119]
	v_pk_fma_f32 v[4:5], v[4:5], v[12:13], v[116:117]
	v_addc_co_u32_e32 v9, vcc, 0, v9, vcc
	v_cvt_pk_bf16_f32 v4, v4, v5
	v_cvt_pk_bf16_f32 v5, v6, v7
	global_store_dwordx2 v[8:9], v[4:5], off offset:1024
	s_waitcnt vmcnt(5)
	v_pk_mul_f32 v[0:1], v[0:1], v[120:121]
	s_load_dwordx2 s[4:5], s[0:1], 0x108
	v_pk_mul_f32 v[2:3], v[2:3], v[122:123]
	s_waitcnt vmcnt(4)
	v_pk_add_f32 v[4:5], v[126:127], 1.0 op_sel_hi:[1,0]
	v_pk_add_f32 v[6:7], v[124:125], 1.0 op_sel_hi:[1,0]
	s_waitcnt lgkmcnt(0)
	s_add_u32 s4, s4, s8
	s_addc_u32 s5, s5, s9
	v_lshl_add_u64 v[16:17], s[4:5], 0, v[34:35]
	v_add_co_u32_e32 v16, vcc, 0x3000000, v16
	s_waitcnt vmcnt(3)
	v_pk_fma_f32 v[2:3], v[2:3], v[4:5], v[130:131]
	v_pk_fma_f32 v[0:1], v[0:1], v[6:7], v[128:129]
	v_addc_co_u32_e32 v17, vcc, 0, v17, vcc
	v_cvt_pk_bf16_f32 v0, v0, v1
	v_cvt_pk_bf16_f32 v1, v2, v3
	global_store_dwordx2 v[16:17], v[0:1], off offset:1536

; __device__ __forceinline__ float rsq_f(float x) { return __builtin_amdgcn_rsqf(x); }
; __device__ __forceinline__ float* karg_out() { return *(volatile KAS fptr_t*)((const KAS char*)__builtin_amdgcn_kernarg_segment_ptr() + 256); }
; __device__ __forceinline__ unsigned char* karg_ws() { return *(volatile KAS ucptr_t*)((const KAS char*)__builtin_amdgcn_kernarg_segment_ptr() + 264); }
; #define lane opq(lane_now())
; template <int MODE>
; __device__ __forceinline__ void sample_norm_rows(const float* gvec, int ish, int gw, int lane) {
;     if (gw >= NS) return;
;     const int row = MPR + gw; float* X = karg_out() + (size_t)row * D;
;     f32x4 v[4]; float s = 0.f;
; #pragma unroll
;     for (int j = 0; j < 4; ++j) { v[j] = *(const f32x4*)(X + 4 * (lane + 64 * j)); s += (v[j][0] * v[j][0] + v[j][1] * v[j][1]) + (v[j][2] * v[j][2] + v[j][3] * v[j][3]); }
;     const float rstd = rsq_f(wave_sum(s) * (1.f / D) + EPS);
;     const float* sh = (const float*)(karg_ws() + WS_ADA) + (size_t)cond_of_row(row) * NADA + ish * D;
.LBB0_2101:
	s_or_b64 exec, exec, s[4:5]
	s_waitcnt lgkmcnt(0)
	s_barrier
	s_load_dwordx2 s[12:13], s[0:1], 0xe0
	v_readlane_b32 s4, v238, 8
	v_readlane_b32 s5, v238, 9
	v_mov_b32_e32 v0, v166
	s_andn2_b64 vcc, exec, s[4:5]
	v_cndmask_b32_e64 v1, 0, 1, s[4:5]
	v_cmp_ne_u32_e64 s[8:9], 1, v1
	s_cbranch_vccnz .LBB0_2103
	s_load_dwordx2 s[4:5], s[0:1], 0x100
	s_add_i32 s10, s70, 0x4000
	s_ashr_i32 s11, s10, 31
	v_lshlrev_b32_e32 v8, 2, v0
	s_lshl_b64 s[6:7], s[10:11], 12
	s_waitcnt lgkmcnt(0)
	s_add_u32 s4, s4, s6
	v_ashrrev_i32_e32 v9, 31, v8
	s_addc_u32 s5, s5, s7
	v_lshlrev_b64 v[26:27], 2, v[8:9]
	v_lshl_add_u64 v[18:19], s[4:5], 0, v[26:27]
	global_load_dwordx4 v[10:13], v[18:19], off
	global_load_dwordx4 v[14:17], v[18:19], off offset:1024
	global_load_dwordx4 v[0:3], v[18:19], off offset:3072
	global_load_dwordx4 v[4:7], v[18:19], off offset:2048
	s_load_dwordx2 s[4:5], s[0:1], 0x108
	s_ashr_i32 s3, s10, 11
	s_add_i32 s6, s70, 8
	s_cmp_lt_i32 s70, 0
	s_cselect_b32 s3, s3, s6
	s_mul_hi_i32 s6, s3, 0x9000
	s_mul_i32 s3, s3, 0x9000
	s_waitcnt lgkmcnt(0)
	s_add_u32 s3, s4, s3
	s_addc_u32 s7, s5, s6
	s_add_u32 s4, s3, 0x2906000
	s_addc_u32 s5, s7, 0
	s_add_u32 s6, s3, 0x2907000
	s_addc_u32 s7, s7, 0
	v_lshl_add_u64 v[92:93], s[6:7], 0, v[26:27]
	v_lshl_add_u64 v[30:31], s[12:13], 0, v[26:27]
	global_load_dwordx4 v[18:21], v[92:93], off
	v_lshl_add_u64 v[94:95], s[4:5], 0, v[26:27]
	global_load_dwordx4 v[22:25], v[30:31], off
	v_mov_b32_e32 v49, 0x358637bd
	global_load_dwordx4 v[26:29], v[94:95], off
	global_load_dwordx4 v[96:99], v[30:31], off offset:1024
	global_load_dwordx4 v[100:103], v[92:93], off offset:1024
	global_load_dwordx4 v[104:107], v[94:95], off offset:1024
	global_load_dwordx4 v[108:111], v[30:31], off offset:2048
	global_load_dwordx4 v[112:115], v[92:93], off offset:2048
	global_load_dwordx4 v[116:119], v[94:95], off offset:2048
	global_load_dwordx4 v[120:123], v[30:31], off offset:3072
	global_load_dwordx4 v[124:127], v[92:93], off offset:3072
	global_load_dwordx4 v[128:131], v[94:95], off offset:3072
	v_lshlrev_b64 v[34:35], 1, v[8:9]
	s_load_dwordx2 s[12:13], s[0:1], 0x108
	s_lshl_b64 s[10:11], s[10:11], 11
	s_mov_b32 s3, 0x3000000
	v_add_u32_e32 v32, 0x100, v8
	v_ashrrev_i32_e32 v33, 31, v32
	s_waitcnt lgkmcnt(0)
	s_add_u32 s12, s12, s10
	s_addc_u32 s13, s13, s11
	v_lshl_add_u64 v[36:37], s[12:13], 0, v[34:35]
	v_add_co_u32_e32 v36, vcc, s3, v36
	v_lshlrev_b64 v[32:33], 2, v[32:33]
	s_nop 0
	v_addc_co_u32_e32 v37, vcc, 0, v37, vcc
	s_waitcnt vmcnt(15)
	v_pk_mul_f32 v[38:39], v[12:13], v[12:13]
	v_pk_mul_f32 v[40:41], v[10:11], v[10:11]
	s_waitcnt vmcnt(14)
	v_pk_mul_f32 v[42:43], v[16:17], v[16:17]
	v_pk_mul_f32 v[44:45], v[14:15], v[14:15]
	v_pk_mov_b32 v[50:51], v[40:41], v[38:39] op_sel:[1,0]
	v_mov_b32_e32 v41, v39
	v_pk_mov_b32 v[38:39], v[44:45], v[42:43] op_sel:[1,0]
	v_mov_b32_e32 v45, v43
	s_waitcnt vmcnt(12)
	v_mul_f32_e32 v46, v5, v5
	v_mul_f32_e32 v48, v7, v7
	v_pk_add_f32 v[40:41], v[50:51], v[40:41]
	v_pk_add_f32 v[38:39], v[38:39], v[44:45]
	v_mul_f32_e32 v9, v0, v0
	v_mul_f32_e32 v52, v1, v1
	v_mul_f32_e32 v53, v2, v2
	v_mul_f32_e32 v54, v3, v3
	v_pk_fma_f32 v[42:43], v[4:5], v[4:5], v[46:47] op_sel_hi:[1,1,0]
	v_pk_fma_f32 v[46:47], v[6:7], v[6:7], v[48:49] op_sel_hi:[1,1,0]
	v_pk_add_f32 v[40:41], v[40:41], v[40:41] op_sel:[0,1] op_sel_hi:[1,0]
	v_pk_add_f32 v[38:39], v[38:39], v[38:39] op_sel:[0,1] op_sel_hi:[1,0]
	v_mov_b32_e32 v43, v53
	v_mov_b32_e32 v47, v54
	v_mov_b32_e32 v41, v9
	v_mov_b32_e32 v39, v52
	v_pk_add_f32 v[42:43], v[42:43], v[46:47]
	v_pk_add_f32 v[38:39], v[40:41], v[38:39]
	s_waitcnt vmcnt(11)
; __device__ __forceinline__ unsigned pk2(float lo, float hi) { f32x2_t v = {lo, hi}; bf16x2_t b = __builtin_convertvector(v, bf16x2_t); return __builtin_bit_cast(unsigned, b); }
; __device__ __forceinline__ float rsq_f(float x) { return __builtin_amdgcn_rsqf(x); }
; __device__ __forceinline__ unsigned char* karg_ws() { return *(volatile KAS ucptr_t*)((const KAS char*)__builtin_amdgcn_kernarg_segment_ptr() + 264); }
; #define lane opq(lane_now())
; template <int MODE>
; __device__ __forceinline__ void sample_norm_rows(const float* gvec, int ish, int gw, int lane) {
;     ...
;     const float rstd = rsq_f(wave_sum(s) * (1.f / D) + EPS);
;     const float* sh = (const float*)(karg_ws() + WS_ADA) + (size_t)cond_of_row(row) * NADA + ish * D;
; #pragma unroll
;     for (int j = 0; j < 4; ++j) { const int col = 4 * (lane + 64 * j); const f32x4 g = *(const f32x4*)(gvec + col);
;         if (MODE == 0) { const f32x4 y = (v[j] * rstd * g) * (*(const f32x4*)(sh + D + col) + 1.f) + *(const f32x4*)(sh + col);
;             u32x2 o; o.x = pk2(y[0], y[1]); o.y = pk2(y[2], y[3]); *(u32x2*)((bf16*)(karg_ws() + WS_H) + (size_t)row * D + col) = o; }
;         else *(f32x4*)(X + col) = v[j] * rstd * g; }
	v_pk_add_f32 v[20:21], v[20:21], 1.0 op_sel_hi:[1,0]
	v_pk_add_f32 v[38:39], v[38:39], v[42:43]
	v_pk_add_f32 v[18:19], v[18:19], 1.0 op_sel_hi:[1,0]
	v_add_f32_e32 v9, v38, v39
	s_nop 1
	v_add_f32_dpp v9, v9, v9 quad_perm:[1,0,3,2] row_mask:0xf bank_mask:0xf bound_ctrl:1
	s_nop 1
	v_add_f32_dpp v9, v9, v9 quad_perm:[2,3,0,1] row_mask:0xf bank_mask:0xf bound_ctrl:1
	s_nop 1
	v_add_f32_dpp v9, v9, v9 row_half_mirror row_mask:0xf bank_mask:0xf bound_ctrl:1
	s_nop 1
	v_add_f32_dpp v9, v9, v9 row_mirror row_mask:0xf bank_mask:0xf bound_ctrl:1
	s_nop 0
	v_readlane_b32 s14, v9, 16
	v_readlane_b32 s15, v9, 48
	v_readlane_b32 s12, v9, 0
	v_readlane_b32 s13, v9, 32
	v_mov_b32_e32 v38, s14
	v_mov_b32_e32 v39, s15
	v_pk_add_f32 v[38:39], s[12:13], v[38:39]
	s_nop 0
	v_add_f32_e32 v9, v38, v39
	v_fmac_f32_e32 v49, 0x3a800000, v9
	v_rsq_f32_e32 v38, v49
	s_nop 0
	v_pk_mul_f32 v[12:13], v[12:13], v[38:39] op_sel_hi:[1,0]
	v_pk_mul_f32 v[10:11], v[10:11], v[38:39] op_sel_hi:[1,0]
	s_waitcnt vmcnt(10)
	v_pk_mul_f32 v[12:13], v[24:25], v[12:13]
	v_pk_mul_f32 v[10:11], v[22:23], v[10:11]
	s_waitcnt vmcnt(9)
	v_pk_fma_f32 v[12:13], v[20:21], v[12:13], v[28:29]
	v_pk_fma_f32 v[10:11], v[18:19], v[10:11], v[26:27]
	v_cvt_pk_bf16_f32 v10, v10, v11
	v_cvt_pk_bf16_f32 v11, v12, v13
	global_store_dwordx2 v[36:37], v[10:11], off
	v_pk_mul_f32 v[16:17], v[16:17], v[38:39] op_sel_hi:[1,0]
	s_load_dwordx2 s[12:13], s[0:1], 0x108
	v_pk_mul_f32 v[14:15], v[14:15], v[38:39] op_sel_hi:[1,0]
	v_add_u32_e32 v26, 0x200, v8
	v_ashrrev_i32_e32 v27, 31, v26
	v_lshlrev_b64 v[26:27], 2, v[26:27]
	s_waitcnt lgkmcnt(0)
	s_add_u32 s12, s12, s10
	s_addc_u32 s13, s13, s11
	v_lshl_add_u64 v[28:29], s[12:13], 0, v[34:35]
	v_add_co_u32_e32 v28, vcc, s3, v28
	v_add_u32_e32 v8, 0x300, v8
	s_nop 0
	v_addc_co_u32_e32 v29, vcc, 0, v29, vcc
	v_ashrrev_i32_e32 v9, 31, v8
	v_pk_mul_f32 v[6:7], v[6:7], v[38:39] op_sel_hi:[1,0]
	v_pk_mul_f32 v[4:5], v[4:5], v[38:39] op_sel_hi:[1,0]
	v_pk_mul_f32 v[2:3], v[2:3], v[38:39] op_sel_hi:[1,0]
	v_pk_mul_f32 v[0:1], v[0:1], v[38:39] op_sel_hi:[1,0]
	s_waitcnt vmcnt(9)
	v_pk_mul_f32 v[10:11], v[96:97], v[14:15]
	v_pk_mul_f32 v[12:13], v[98:99], v[16:17]
	s_waitcnt vmcnt(8)
	v_pk_add_f32 v[14:15], v[102:103], 1.0 op_sel_hi:[1,0]
	v_pk_add_f32 v[16:17], v[100:101], 1.0 op_sel_hi:[1,0]
	s_waitcnt vmcnt(7)
	v_pk_fma_f32 v[12:13], v[14:15], v[12:13], v[106:107]
	v_pk_fma_f32 v[10:11], v[16:17], v[10:11], v[104:105]
	v_cvt_pk_bf16_f32 v10, v10, v11
	v_cvt_pk_bf16_f32 v11, v12, v13
	global_store_dwordx2 v[28:29], v[10:11], off offset:512
	v_lshlrev_b64 v[22:23], 2, v[8:9]
	s_load_dwordx2 s[12:13], s[0:1], 0x108
	s_waitcnt lgkmcnt(0)
	s_add_u32 s12, s12, s10
	s_addc_u32 s13, s13, s11
	v_lshl_add_u64 v[8:9], s[12:13], 0, v[34:35]
	v_add_co_u32_e32 v8, vcc, s3, v8
	s_waitcnt vmcnt(7)
	v_pk_mul_f32 v[4:5], v[4:5], v[108:109]
	v_pk_mul_f32 v[6:7], v[6:7], v[110:111]
	s_waitcnt vmcnt(6)
	v_pk_add_f32 v[10:11], v[114:115], 1.0 op_sel_hi:[1,0]
	v_pk_add_f32 v[12:13], v[112:113], 1.0 op_sel_hi:[1,0]
	s_waitcnt vmcnt(5)
	v_pk_fma_f32 v[6:7], v[6:7], v[10:11], v[118:119]
	v_pk_fma_f32 v[4:5], v[4:5], v[12:13], v[116:117]
	v_addc_co_u32_e32 v9, vcc, 0, v9, vcc
	v_cvt_pk_bf16_f32 v4, v4, v5
	v_cvt_pk_bf16_f32 v5, v6, v7
	global_store_dwordx2 v[8:9], v[4:5], off offset:1024
	s_waitcnt vmcnt(5)
	v_pk_mul_f32 v[0:1], v[0:1], v[120:121]
	s_load_dwordx2 s[4:5], s[0:1], 0x108
	v_pk_mul_f32 v[2:3], v[2:3], v[122:123]
	s_waitcnt vmcnt(4)
	v_pk_add_f32 v[4:5], v[126:127], 1.0 op_sel_hi:[1,0]
	v_pk_add_f32 v[6:7], v[124:125], 1.0 op_sel_hi:[1,0]
	s_waitcnt lgkmcnt(0)
	s_add_u32 s4, s4, s10
	s_addc_u32 s5, s5, s11
	v_lshl_add_u64 v[16:17], s[4:5], 0, v[34:35]
	v_add_co_u32_e32 v16, vcc, 0x3000000, v16
	s_waitcnt vmcnt(3)
	v_pk_fma_f32 v[2:3], v[2:3], v[4:5], v[130:131]
	v_pk_fma_f32 v[0:1], v[0:1], v[6:7], v[128:129]
	v_addc_co_u32_e32 v17, vcc, 0, v17, vcc
	v_cvt_pk_bf16_f32 v0, v0, v1
	v_cvt_pk_bf16_f32 v1, v2, v3
	global_store_dwordx2 v[16:17], v[0:1], off offset:1536
